# speedup vs baseline: 1.0560x; 1.0091x over previous
.LBB0_600:
	v_mov_b32_e32 v171, v204
	v_lshl_add_u64 v[138:139], v[130:131], 0, s[8:9]
	v_lshlrev_b32_e32 v0, 4, v171
	v_ashrrev_i32_e32 v144, 5, v171
	v_lshl_add_u64 v[138:139], s[6:7], 1, v[138:139]
	v_and_b32_e32 v0, 0x1f0, v0
	v_ashrrev_i32_e32 v145, 31, v144
	v_lshl_add_u64 v[168:169], v[138:139], 0, v[0:1]
	v_lshlrev_b64 v[138:139], 12, v[144:145]
	v_lshl_add_u64 v[138:139], v[168:169], 0, v[138:139]
	s_waitcnt vmcnt(0)
	s_barrier
	flat_load_dwordx4 v[196:199], v[138:139]
	v_mul_lo_u32 v144, v144, s72
	v_add_u32_e32 v172, v0, v144
	s_movk_i32 s0, 0xffc0
	v_add_u32_e32 v140, 0x200, v171
	v_ashrrev_i32_e32 v146, 5, v140
	v_ashrrev_i32_e32 v147, 31, v146
	v_lshlrev_b64 v[140:141], 12, v[146:147]
	v_lshl_add_u64 v[140:141], v[168:169], 0, v[140:141]
	flat_load_dwordx4 v[206:209], v[140:141]
	v_mul_lo_u32 v146, v146, s72
	v_add_u32_e32 v173, v0, v146
	v_add_u32_e32 v142, 0x400, v171
	v_ashrrev_i32_e32 v148, 5, v142
	v_ashrrev_i32_e32 v149, 31, v148
	v_lshlrev_b64 v[142:143], 12, v[148:149]
	v_lshl_add_u64 v[142:143], v[168:169], 0, v[142:143]
	flat_load_dwordx4 v[218:221], v[142:143]
	v_mul_lo_u32 v148, v148, s72
	v_add_u32_e32 v174, v0, v148
	v_add_u32_e32 v144, 0x600, v171
	v_ashrrev_i32_e32 v150, 5, v144
	v_ashrrev_i32_e32 v151, 31, v150
	v_lshlrev_b64 v[144:145], 12, v[150:151]
	v_lshl_add_u64 v[144:145], v[168:169], 0, v[144:145]
	flat_load_dwordx4 v[222:225], v[144:145]
	v_mul_lo_u32 v150, v150, s72
	v_add_u32_e32 v175, v0, v150
	v_add_u32_e32 v146, 0x800, v171
	v_ashrrev_i32_e32 v152, 5, v146
	v_ashrrev_i32_e32 v153, 31, v152
	v_lshlrev_b64 v[146:147], 12, v[152:153]
	v_lshl_add_u64 v[146:147], v[168:169], 0, v[146:147]
	flat_load_dwordx4 v[226:229], v[146:147]
	v_mul_lo_u32 v152, v152, s72
	v_add_u32_e32 v176, v0, v152
	v_add_u32_e32 v148, 0xa00, v171
	v_ashrrev_i32_e32 v154, 5, v148
	v_ashrrev_i32_e32 v155, 31, v154
	v_lshlrev_b64 v[148:149], 12, v[154:155]
	v_lshl_add_u64 v[148:149], v[168:169], 0, v[148:149]
	flat_load_dwordx4 v[230:233], v[148:149]
	v_mul_lo_u32 v154, v154, s72
	v_add_u32_e32 v177, v0, v154
	v_add_u32_e32 v150, 0xc00, v171
	v_ashrrev_i32_e32 v156, 5, v150
	v_ashrrev_i32_e32 v157, 31, v156
	v_lshlrev_b64 v[150:151], 12, v[156:157]
	v_lshl_add_u64 v[150:151], v[168:169], 0, v[150:151]
	flat_load_dwordx4 v[234:237], v[150:151]
	v_mul_lo_u32 v156, v156, s72
	v_add_u32_e32 v178, v0, v156
	v_add_u32_e32 v152, 0xe00, v171
	v_ashrrev_i32_e32 v158, 5, v152
	v_ashrrev_i32_e32 v159, 31, v158
	v_lshlrev_b64 v[152:153], 12, v[158:159]
	v_lshl_add_u64 v[152:153], v[168:169], 0, v[152:153]
	flat_load_dwordx4 v[238:241], v[152:153]
	v_mul_lo_u32 v158, v158, s72
	v_add_u32_e32 v179, v0, v158
	s_waitcnt vmcnt(0) lgkmcnt(0)
	ds_write_b128 v172, v[196:199]
	ds_write_b128 v173, v[206:209]
	ds_write_b128 v174, v[218:221]
	ds_write_b128 v175, v[222:225]
	ds_write_b128 v176, v[226:229]
	ds_write_b128 v177, v[230:233]
	ds_write_b128 v178, v[234:237]
	ds_write_b128 v179, v[238:241]
	v_add_u32_e32 v154, 0x1000, v171
	v_ashrrev_i32_e32 v160, 5, v154
	v_ashrrev_i32_e32 v161, 31, v160
	v_lshlrev_b64 v[154:155], 12, v[160:161]
	v_lshl_add_u64 v[154:155], v[168:169], 0, v[154:155]
	flat_load_dwordx4 v[196:199], v[154:155]
	v_mul_lo_u32 v160, v160, s72
	v_add_u32_e32 v180, v0, v160
	v_add_u32_e32 v156, 0x1200, v171
	v_ashrrev_i32_e32 v162, 5, v156
	v_ashrrev_i32_e32 v163, 31, v162
	v_lshlrev_b64 v[156:157], 12, v[162:163]
	v_lshl_add_u64 v[156:157], v[168:169], 0, v[156:157]
	flat_load_dwordx4 v[206:209], v[156:157]
	v_mul_lo_u32 v162, v162, s72
	v_add_u32_e32 v181, v0, v162
	v_add_u32_e32 v158, 0x1400, v171
	v_ashrrev_i32_e32 v164, 5, v158
	v_ashrrev_i32_e32 v165, 31, v164
	v_lshlrev_b64 v[158:159], 12, v[164:165]
	v_lshl_add_u64 v[158:159], v[168:169], 0, v[158:159]
	flat_load_dwordx4 v[218:221], v[158:159]
	v_mul_lo_u32 v164, v164, s72
	v_add_u32_e32 v182, v0, v164
	v_add_u32_e32 v160, 0x1600, v171
	v_ashrrev_i32_e32 v166, 5, v160
	v_ashrrev_i32_e32 v167, 31, v166
	v_lshlrev_b64 v[160:161], 12, v[166:167]
	v_lshl_add_u64 v[160:161], v[168:169], 0, v[160:161]
	flat_load_dwordx4 v[222:225], v[160:161]
	v_mul_lo_u32 v166, v166, s72
	v_add_u32_e32 v183, v0, v166
	v_add_u32_e32 v162, 0x1800, v171
	v_ashrrev_i32_e32 v184, 5, v162
	v_ashrrev_i32_e32 v185, 31, v184
	v_lshlrev_b64 v[162:163], 12, v[184:185]
	v_lshl_add_u64 v[162:163], v[168:169], 0, v[162:163]
	flat_load_dwordx4 v[226:229], v[162:163]
	v_mul_lo_u32 v170, v184, s72
	v_add_u32_e32 v184, v0, v170
	v_add_u32_e32 v164, 0x1a00, v171
	v_ashrrev_i32_e32 v166, 5, v164
	v_ashrrev_i32_e32 v167, 31, v166
	v_lshlrev_b64 v[164:165], 12, v[166:167]
	v_lshl_add_u64 v[164:165], v[168:169], 0, v[164:165]
	flat_load_dwordx4 v[230:233], v[164:165]
	v_mul_lo_u32 v166, v166, s72
	v_add_u32_e32 v185, v0, v166
	v_add_u32_e32 v166, 0x1c00, v171
	v_ashrrev_i32_e32 v186, 5, v166
	v_ashrrev_i32_e32 v187, 31, v186
	v_lshlrev_b64 v[166:167], 12, v[186:187]
	v_lshl_add_u64 v[166:167], v[168:169], 0, v[166:167]
	flat_load_dwordx4 v[234:237], v[166:167]
	v_mul_lo_u32 v170, v186, s72
	v_add_u32_e32 v186, v0, v170
	v_add_u32_e32 v170, 0x1e00, v171
	v_ashrrev_i32_e32 v192, 5, v170
	v_ashrrev_i32_e32 v193, 31, v192
	v_mul_lo_u32 v170, v192, s72
	v_add_u32_e32 v0, v0, v170
	v_and_b32_e32 v170, 15, v171
	v_ashrrev_i32_e32 v187, 2, v171
	v_and_or_b32 v170, v187, s0, v170
	s_movk_i32 s0, 0xc0
	v_lshlrev_b64 v[188:189], 12, v[192:193]
	v_lshl_add_u64 v[168:169], v[168:169], 0, v[188:189]
	flat_load_dwordx4 v[238:241], v[168:169]
	s_waitcnt vmcnt(0) lgkmcnt(0)
	ds_write_b128 v180, v[196:199]
	ds_write_b128 v181, v[206:209]
	ds_write_b128 v182, v[218:221]
	ds_write_b128 v183, v[222:225]
	ds_write_b128 v184, v[226:229]
	ds_write_b128 v185, v[230:233]
	ds_write_b128 v186, v[234:237]
	ds_write_b128 v0, v[238:241]
	v_bfe_u32 v190, v171, 4, 2
	v_lshlrev_b32_e32 v187, 3, v190
	v_and_or_b32 v189, v171, s0, v187
	v_and_b32_e32 v187, 64, v205
	v_xor_b32_e32 v171, 16, v205
	v_add_u32_e32 v188, 64, v187
	v_cmp_lt_i32_e32 vcc, v171, v188
	s_waitcnt lgkmcnt(0)
	s_barrier
	v_cndmask_b32_e32 v171, v205, v171, vcc
	v_lshlrev_b32_e32 v187, 2, v171
	v_xor_b32_e32 v171, 32, v205
	v_cmp_lt_i32_e32 vcc, v171, v188
	s_nop 1
	v_cndmask_b32_e32 v171, v205, v171, vcc
	v_cmp_eq_u32_e32 vcc, 0, v190
	v_mul_lo_u32 v190, v170, s72
	v_lshlrev_b32_e32 v188, 2, v171
	v_add_u32_e32 v171, v189, v190
	ds_read2_b64 v[192:195], v171 offset1:4
	s_waitcnt lgkmcnt(0)
	v_lshlrev_b32_e32 v191, 16, v192
	v_add_f32_e32 v191, v126, v191
	v_and_b32_e32 v126, 0xffff0000, v192
	v_add_f32_e32 v192, v127, v126
	v_lshlrev_b32_e32 v126, 16, v193
	v_add_f32_e32 v128, v128, v126
	v_and_b32_e32 v126, 0xffff0000, v193
	v_add_f32_e32 v129, v129, v126
	v_cvt_pk_bf16_f32 v126, v191, v192
	v_mul_f32_e32 v192, v192, v192
	v_fmac_f32_e32 v192, v191, v191
	v_cvt_pk_bf16_f32 v127, v128, v129
	v_fmac_f32_e32 v192, v128, v128
	v_lshlrev_b32_e32 v128, 16, v194
	v_add_f32_e32 v128, v122, v128
	v_and_b32_e32 v122, 0xffff0000, v194
	v_fmac_f32_e32 v192, v129, v129
	v_add_f32_e32 v129, v123, v122
	v_lshlrev_b32_e32 v122, 16, v195
	v_add_f32_e32 v124, v124, v122
	v_and_b32_e32 v122, 0xffff0000, v195
	v_add_f32_e32 v125, v125, v122
	v_cvt_pk_bf16_f32 v122, v128, v129
	v_cvt_pk_bf16_f32 v123, v124, v125
	ds_write2_b64 v171, v[126:127], v[122:123] offset1:4
	v_mul_f32_e32 v122, v129, v129
	v_fmac_f32_e32 v122, v128, v128
	v_fmac_f32_e32 v122, v124, v124
	v_fmac_f32_e32 v122, v125, v125
	v_add_f32_e32 v126, v192, v122
	ds_read2_b64 v[122:125], v171 offset0:32 offset1:36
	s_waitcnt lgkmcnt(0)
	v_lshlrev_b32_e32 v127, 16, v122
	v_add_f32_e32 v127, v118, v127
	v_and_b32_e32 v118, 0xffff0000, v122
	v_add_f32_e32 v122, v119, v118
	v_lshlrev_b32_e32 v118, 16, v123
	v_add_f32_e32 v120, v120, v118
	v_and_b32_e32 v118, 0xffff0000, v123
	v_add_f32_e32 v121, v121, v118
	v_cvt_pk_bf16_f32 v118, v127, v122
	v_mul_f32_e32 v122, v122, v122
	v_fmac_f32_e32 v122, v127, v127
	v_fmac_f32_e32 v122, v120, v120
	v_cvt_pk_bf16_f32 v119, v120, v121
	v_fmac_f32_e32 v122, v121, v121
	v_lshlrev_b32_e32 v121, 16, v124
	v_add_f32_e32 v121, v114, v121
	v_and_b32_e32 v114, 0xffff0000, v124
	v_add_f32_e32 v120, v126, v122
	v_add_f32_e32 v122, v115, v114
	v_lshlrev_b32_e32 v114, 16, v125
	v_add_f32_e32 v116, v116, v114
	v_and_b32_e32 v114, 0xffff0000, v125
	v_add_f32_e32 v117, v117, v114
	v_cvt_pk_bf16_f32 v114, v121, v122
	v_cvt_pk_bf16_f32 v115, v116, v117
	ds_write2_b64 v171, v[118:119], v[114:115] offset0:32 offset1:36
	v_mul_f32_e32 v114, v122, v122
	v_fmac_f32_e32 v114, v121, v121
	v_fmac_f32_e32 v114, v116, v116
	v_fmac_f32_e32 v114, v117, v117
	v_add_f32_e32 v114, v120, v114
	ds_bpermute_b32 v115, v187, v114
	v_ashrrev_i32_e32 v171, 31, v170
	s_waitcnt lgkmcnt(0)
	v_add_f32_e32 v116, v114, v115
	ds_bpermute_b32 v117, v188, v116
	v_lshl_add_u64 v[114:115], s[4:5], 3, v[136:137]
	s_and_saveexec_b64 s[4:5], vcc
	s_cbranch_execz .LBB0_602
	s_waitcnt lgkmcnt(0)
	v_add_f32_e32 v116, v116, v117
	s_mov_b32 s0, 0x49800000
	v_fma_f32 v116, v116, s0, 0.5
	v_trunc_f32_e32 v116, v116
	v_mul_f32_e32 v117, 0x2f800000, v116
	v_floor_f32_e32 v117, v117
	v_fmac_f32_e32 v116, 0xcf800000, v117
	v_cvt_u32_f32_e32 v116, v116
	v_cvt_u32_f32_e32 v117, v117
	v_lshl_add_u64 v[118:119], v[170:171], 3, v[114:115]
	flat_atomic_add_x2 v[118:119], v[116:117]

.LBB0_668:
	v_mov_b32_e32 v171, v204
	s_lshl_b64 s[0:1], s[6:7], 12
	v_lshl_add_u64 v[138:139], v[130:131], 0, s[0:1]
	v_lshlrev_b32_e32 v0, 4, v171
	v_ashrrev_i32_e32 v144, 5, v171
	v_lshl_add_u64 v[138:139], s[8:9], 1, v[138:139]
	v_and_b32_e32 v0, 0x1f0, v0
	v_ashrrev_i32_e32 v145, 31, v144
	v_lshl_add_u64 v[168:169], v[138:139], 0, v[0:1]
	v_lshlrev_b64 v[138:139], 12, v[144:145]
	v_lshl_add_u64 v[138:139], v[168:169], 0, v[138:139]
	s_waitcnt vmcnt(0)
	s_barrier
	flat_load_dwordx4 v[196:199], v[138:139]
	v_mul_lo_u32 v144, v144, s72
	v_add_u32_e32 v172, v0, v144
	s_movk_i32 s0, 0xffc0
	v_add_u32_e32 v140, 0x200, v171
	v_ashrrev_i32_e32 v146, 5, v140
	v_ashrrev_i32_e32 v147, 31, v146
	v_lshlrev_b64 v[140:141], 12, v[146:147]
	v_lshl_add_u64 v[140:141], v[168:169], 0, v[140:141]
	flat_load_dwordx4 v[206:209], v[140:141]
	v_mul_lo_u32 v146, v146, s72
	v_add_u32_e32 v173, v0, v146
	v_add_u32_e32 v142, 0x400, v171
	v_ashrrev_i32_e32 v148, 5, v142
	v_ashrrev_i32_e32 v149, 31, v148
	v_lshlrev_b64 v[142:143], 12, v[148:149]
	v_lshl_add_u64 v[142:143], v[168:169], 0, v[142:143]
	flat_load_dwordx4 v[218:221], v[142:143]
	v_mul_lo_u32 v148, v148, s72
	v_add_u32_e32 v174, v0, v148
	v_add_u32_e32 v144, 0x600, v171
	v_ashrrev_i32_e32 v150, 5, v144
	v_ashrrev_i32_e32 v151, 31, v150
	v_lshlrev_b64 v[144:145], 12, v[150:151]
	v_lshl_add_u64 v[144:145], v[168:169], 0, v[144:145]
	flat_load_dwordx4 v[222:225], v[144:145]
	v_mul_lo_u32 v150, v150, s72
	v_add_u32_e32 v175, v0, v150
	v_add_u32_e32 v146, 0x800, v171
	v_ashrrev_i32_e32 v152, 5, v146
	v_ashrrev_i32_e32 v153, 31, v152
	v_lshlrev_b64 v[146:147], 12, v[152:153]
	v_lshl_add_u64 v[146:147], v[168:169], 0, v[146:147]
	flat_load_dwordx4 v[226:229], v[146:147]
	v_mul_lo_u32 v152, v152, s72
	v_add_u32_e32 v176, v0, v152
	v_add_u32_e32 v148, 0xa00, v171
	v_ashrrev_i32_e32 v154, 5, v148
	v_ashrrev_i32_e32 v155, 31, v154
	v_lshlrev_b64 v[148:149], 12, v[154:155]
	v_lshl_add_u64 v[148:149], v[168:169], 0, v[148:149]
	flat_load_dwordx4 v[230:233], v[148:149]
	v_mul_lo_u32 v154, v154, s72
	v_add_u32_e32 v177, v0, v154
	v_add_u32_e32 v150, 0xc00, v171
	v_ashrrev_i32_e32 v156, 5, v150
	v_ashrrev_i32_e32 v157, 31, v156
	v_lshlrev_b64 v[150:151], 12, v[156:157]
	v_lshl_add_u64 v[150:151], v[168:169], 0, v[150:151]
	flat_load_dwordx4 v[234:237], v[150:151]
	v_mul_lo_u32 v156, v156, s72
	v_add_u32_e32 v178, v0, v156
	v_add_u32_e32 v152, 0xe00, v171
	v_ashrrev_i32_e32 v158, 5, v152
	v_ashrrev_i32_e32 v159, 31, v158
	v_lshlrev_b64 v[152:153], 12, v[158:159]
	v_lshl_add_u64 v[152:153], v[168:169], 0, v[152:153]
	flat_load_dwordx4 v[238:241], v[152:153]
	v_mul_lo_u32 v158, v158, s72
	v_add_u32_e32 v179, v0, v158
	s_waitcnt vmcnt(0) lgkmcnt(0)
	ds_write_b128 v172, v[196:199]
	ds_write_b128 v173, v[206:209]
	ds_write_b128 v174, v[218:221]
	ds_write_b128 v175, v[222:225]
	ds_write_b128 v176, v[226:229]
	ds_write_b128 v177, v[230:233]
	ds_write_b128 v178, v[234:237]
	ds_write_b128 v179, v[238:241]
	v_add_u32_e32 v154, 0x1000, v171
	v_ashrrev_i32_e32 v160, 5, v154
	v_ashrrev_i32_e32 v161, 31, v160
	v_lshlrev_b64 v[154:155], 12, v[160:161]
	v_lshl_add_u64 v[154:155], v[168:169], 0, v[154:155]
	flat_load_dwordx4 v[196:199], v[154:155]
	v_mul_lo_u32 v160, v160, s72
	v_add_u32_e32 v180, v0, v160
	v_add_u32_e32 v156, 0x1200, v171
	v_ashrrev_i32_e32 v162, 5, v156
	v_ashrrev_i32_e32 v163, 31, v162
	v_lshlrev_b64 v[156:157], 12, v[162:163]
	v_lshl_add_u64 v[156:157], v[168:169], 0, v[156:157]
	flat_load_dwordx4 v[206:209], v[156:157]
	v_mul_lo_u32 v162, v162, s72
	v_add_u32_e32 v181, v0, v162
	v_add_u32_e32 v158, 0x1400, v171
	v_ashrrev_i32_e32 v164, 5, v158
	v_ashrrev_i32_e32 v165, 31, v164
	v_lshlrev_b64 v[158:159], 12, v[164:165]
	v_lshl_add_u64 v[158:159], v[168:169], 0, v[158:159]
	flat_load_dwordx4 v[218:221], v[158:159]
	v_mul_lo_u32 v164, v164, s72
	v_add_u32_e32 v182, v0, v164
	v_add_u32_e32 v160, 0x1600, v171
	v_ashrrev_i32_e32 v166, 5, v160
	v_ashrrev_i32_e32 v167, 31, v166
	v_lshlrev_b64 v[160:161], 12, v[166:167]
	v_lshl_add_u64 v[160:161], v[168:169], 0, v[160:161]
	flat_load_dwordx4 v[222:225], v[160:161]
	v_mul_lo_u32 v166, v166, s72
	v_add_u32_e32 v183, v0, v166
	v_add_u32_e32 v162, 0x1800, v171
	v_ashrrev_i32_e32 v184, 5, v162
	v_ashrrev_i32_e32 v185, 31, v184
	v_lshlrev_b64 v[162:163], 12, v[184:185]
	v_lshl_add_u64 v[162:163], v[168:169], 0, v[162:163]
	flat_load_dwordx4 v[226:229], v[162:163]
	v_mul_lo_u32 v170, v184, s72
	v_add_u32_e32 v184, v0, v170
	v_add_u32_e32 v164, 0x1a00, v171
	v_ashrrev_i32_e32 v166, 5, v164
	v_ashrrev_i32_e32 v167, 31, v166
	v_lshlrev_b64 v[164:165], 12, v[166:167]
	v_lshl_add_u64 v[164:165], v[168:169], 0, v[164:165]
	flat_load_dwordx4 v[230:233], v[164:165]
	v_mul_lo_u32 v166, v166, s72
	v_add_u32_e32 v185, v0, v166
	v_add_u32_e32 v166, 0x1c00, v171
	v_ashrrev_i32_e32 v186, 5, v166
	v_ashrrev_i32_e32 v187, 31, v186
	v_lshlrev_b64 v[166:167], 12, v[186:187]
	v_lshl_add_u64 v[166:167], v[168:169], 0, v[166:167]
	flat_load_dwordx4 v[234:237], v[166:167]
	v_mul_lo_u32 v170, v186, s72
	v_add_u32_e32 v186, v0, v170
	v_add_u32_e32 v170, 0x1e00, v171
	v_ashrrev_i32_e32 v192, 5, v170
	v_ashrrev_i32_e32 v193, 31, v192
	v_mul_lo_u32 v170, v192, s72
	v_add_u32_e32 v0, v0, v170
	v_and_b32_e32 v170, 15, v171
	v_ashrrev_i32_e32 v187, 2, v171
	v_and_or_b32 v170, v187, s0, v170
	s_movk_i32 s0, 0xc0
	v_lshlrev_b64 v[188:189], 12, v[192:193]
	v_lshl_add_u64 v[168:169], v[168:169], 0, v[188:189]
	flat_load_dwordx4 v[238:241], v[168:169]
	s_waitcnt vmcnt(0) lgkmcnt(0)
	ds_write_b128 v180, v[196:199]
	ds_write_b128 v181, v[206:209]
	ds_write_b128 v182, v[218:221]
	ds_write_b128 v183, v[222:225]
	ds_write_b128 v184, v[226:229]
	ds_write_b128 v185, v[230:233]
	ds_write_b128 v186, v[234:237]
	ds_write_b128 v0, v[238:241]
	v_bfe_u32 v190, v171, 4, 2
	v_lshlrev_b32_e32 v187, 3, v190
	v_and_or_b32 v189, v171, s0, v187
	v_and_b32_e32 v187, 64, v205
	v_xor_b32_e32 v171, 16, v205
	v_add_u32_e32 v188, 64, v187
	v_cmp_lt_i32_e32 vcc, v171, v188
	s_waitcnt lgkmcnt(0)
	s_barrier
	v_cndmask_b32_e32 v171, v205, v171, vcc
	v_lshlrev_b32_e32 v187, 2, v171
	v_xor_b32_e32 v171, 32, v205
	v_cmp_lt_i32_e32 vcc, v171, v188
	s_nop 1
	v_cndmask_b32_e32 v171, v205, v171, vcc
	v_cmp_eq_u32_e32 vcc, 0, v190
	v_mul_lo_u32 v190, v170, s72
	v_lshlrev_b32_e32 v188, 2, v171
	v_add_u32_e32 v171, v189, v190
	ds_read2_b64 v[192:195], v171 offset1:4
	s_waitcnt lgkmcnt(0)
	v_lshlrev_b32_e32 v191, 16, v192
	v_add_f32_e32 v191, v126, v191
	v_and_b32_e32 v126, 0xffff0000, v192
	v_add_f32_e32 v192, v127, v126
	v_lshlrev_b32_e32 v126, 16, v193
	v_add_f32_e32 v128, v128, v126
	v_and_b32_e32 v126, 0xffff0000, v193
	v_add_f32_e32 v129, v129, v126
	v_cvt_pk_bf16_f32 v126, v191, v192
	v_mul_f32_e32 v192, v192, v192
	v_fmac_f32_e32 v192, v191, v191
	v_cvt_pk_bf16_f32 v127, v128, v129
	v_fmac_f32_e32 v192, v128, v128
	v_lshlrev_b32_e32 v128, 16, v194
	v_add_f32_e32 v128, v122, v128
	v_and_b32_e32 v122, 0xffff0000, v194
	v_fmac_f32_e32 v192, v129, v129
	v_add_f32_e32 v129, v123, v122
	v_lshlrev_b32_e32 v122, 16, v195
	v_add_f32_e32 v124, v124, v122
	v_and_b32_e32 v122, 0xffff0000, v195
	v_add_f32_e32 v125, v125, v122
	v_cvt_pk_bf16_f32 v122, v128, v129
	v_cvt_pk_bf16_f32 v123, v124, v125
	ds_write2_b64 v171, v[126:127], v[122:123] offset1:4
	v_mul_f32_e32 v122, v129, v129
	v_fmac_f32_e32 v122, v128, v128
	v_fmac_f32_e32 v122, v124, v124
	v_fmac_f32_e32 v122, v125, v125
	v_add_f32_e32 v126, v192, v122
	ds_read2_b64 v[122:125], v171 offset0:32 offset1:36
	s_waitcnt lgkmcnt(0)
	v_lshlrev_b32_e32 v127, 16, v122
	v_add_f32_e32 v127, v118, v127
	v_and_b32_e32 v118, 0xffff0000, v122
	v_add_f32_e32 v122, v119, v118
	v_lshlrev_b32_e32 v118, 16, v123
	v_add_f32_e32 v120, v120, v118
	v_and_b32_e32 v118, 0xffff0000, v123
	v_add_f32_e32 v121, v121, v118
	v_cvt_pk_bf16_f32 v118, v127, v122
	v_mul_f32_e32 v122, v122, v122
	v_fmac_f32_e32 v122, v127, v127
	v_fmac_f32_e32 v122, v120, v120
	v_cvt_pk_bf16_f32 v119, v120, v121
	v_fmac_f32_e32 v122, v121, v121
	v_lshlrev_b32_e32 v121, 16, v124
	v_add_f32_e32 v121, v114, v121
	v_and_b32_e32 v114, 0xffff0000, v124
	v_add_f32_e32 v120, v126, v122
	v_add_f32_e32 v122, v115, v114
	v_lshlrev_b32_e32 v114, 16, v125
	v_add_f32_e32 v116, v116, v114
	v_and_b32_e32 v114, 0xffff0000, v125
	v_add_f32_e32 v117, v117, v114
	v_cvt_pk_bf16_f32 v114, v121, v122
	v_cvt_pk_bf16_f32 v115, v116, v117
	ds_write2_b64 v171, v[118:119], v[114:115] offset0:32 offset1:36
	v_mul_f32_e32 v114, v122, v122
	v_fmac_f32_e32 v114, v121, v121
	v_fmac_f32_e32 v114, v116, v116
	v_fmac_f32_e32 v114, v117, v117
	v_add_f32_e32 v114, v120, v114
	ds_bpermute_b32 v115, v187, v114
	v_ashrrev_i32_e32 v171, 31, v170
	s_waitcnt lgkmcnt(0)
	v_add_f32_e32 v116, v114, v115
	ds_bpermute_b32 v117, v188, v116
	v_lshl_add_u64 v[114:115], s[6:7], 3, v[134:135]
	s_and_saveexec_b64 s[6:7], vcc
	s_cbranch_execz .LBB0_670
	s_waitcnt lgkmcnt(0)
	v_add_f32_e32 v116, v116, v117
	s_mov_b32 s0, 0x49800000
	v_fma_f32 v116, v116, s0, 0.5
	v_trunc_f32_e32 v116, v116
	v_mul_f32_e32 v117, 0x2f800000, v116
	v_floor_f32_e32 v117, v117
	v_fmac_f32_e32 v116, 0xcf800000, v117
	v_cvt_u32_f32_e32 v116, v116
	v_cvt_u32_f32_e32 v117, v117
	v_lshl_add_u64 v[118:119], v[170:171], 3, v[114:115]
	flat_atomic_add_x2 v[118:119], v[116:117]
